# SX1: attention loop: softmax head (row max, cross-half max, lazy m update, 32 scaling FMAs) moved from the Y section into the gaps between the P.V MFMAs of the same wave's X section; on top of Y2
# baseline (speedup 1.0000x reference)
.LBB0_628:
	v_and_b32_e32 v5, 0x3fffffc0, v4
	s_add_i32 s8, 0, 0x18000
	v_lshl_add_u32 v171, v5, 2, s8
	s_add_i32 s8, 0, 0xc000
	s_cmp_lg_u32 s8, -1
	v_and_b32_e32 v169, 63, v4
	v_lshlrev_b32_e32 v4, 4, v4
	s_cselect_b32 s8, s8, 0
	v_and_b32_e32 v4, 0x70, v4
	v_lshl_add_u32 v7, v165, 8, s8
	v_or_b32_e32 v8, 32, v168
	v_xad_u32 v175, v8, v4, v7
	v_or_b32_e32 v8, 64, v168
	v_lshlrev_b32_e32 v5, 4, v169
	v_xad_u32 v176, v8, v4, v7
	v_or_b32_e32 v8, 0x60, v168
	s_mov_b32 s48, 2
	s_mov_b32 s49, 1
	v_lshlrev_b32_e32 v6, 1, v169
	s_mov_b32 s52, 0
	v_xad_u32 v174, v168, v4, v7
	v_xad_u32 v177, v8, v4, v7
	v_lshlrev_b32_e32 v66, 3, v169
	s_movk_i32 s50, 0xc0
	v_and_b32_e32 v67, 0xc0, v5
	v_and_b32_e32 v148, 32, v6
	ds_read_b128 v[4:7], v174 offset:0
	ds_read_b128 v[8:11], v174 offset:0x2000
	ds_read_b128 v[12:15], v175 offset:0
	ds_read_b128 v[42:45], v175 offset:0x2000
	ds_read_b128 v[46:49], v176 offset:0
	ds_read_b128 v[50:53], v176 offset:0x2000
	ds_read_b128 v[54:57], v177 offset:0
	ds_read_b128 v[58:61], v177 offset:0x2000
	s_waitcnt lgkmcnt(4)
	s_nop 0
	v_mfma_f32_32x32x16_bf16 v[84:99], v[4:7], v[128:131], 0
	s_mov_b32 s53, s52
	s_mov_b32 s54, s52
	s_mov_b32 s55, s52
	s_mov_b32 s56, s52
	s_mov_b32 s57, s52
	s_mov_b32 s58, s52
	s_mov_b32 s59, s52
	v_mfma_f32_32x32x16_bf16 v[68:83], v[8:11], v[128:131], 0
	s_mov_b32 s60, s52
	s_mov_b32 s61, s52
	s_mov_b32 s62, s52
	s_mov_b32 s63, s52
	s_mov_b32 s64, s52
	s_mov_b32 s65, s52
	s_mov_b32 s66, s52
	v_mfma_f32_32x32x16_bf16 v[84:99], v[12:15], v[124:127], v[84:99]
	s_mov_b32 s67, s52
	v_mov_b64_e32 v[4:5], s[52:53]
	v_mov_b64_e32 v[6:7], s[54:55]
	v_mov_b64_e32 v[8:9], s[56:57]
	v_mov_b64_e32 v[10:11], s[58:59]
	v_mov_b64_e32 v[12:13], s[60:61]
	v_mov_b64_e32 v[14:15], s[62:63]
	v_mfma_f32_32x32x16_bf16 v[68:83], v[42:45], v[124:127], v[68:83]
	v_mov_b64_e32 v[16:17], s[64:65]
	v_mov_b64_e32 v[18:19], s[66:67]
	ds_read_b128 v[42:45], v174 offset:0x80
	ds_read_b128 v[62:65], v174 offset:0x2080
	ds_read_b128 v[132:135], v175 offset:0x80
	ds_read_b128 v[136:139], v175 offset:0x2080
	s_waitcnt lgkmcnt(4)
	v_mfma_f32_32x32x16_bf16 v[84:99], v[46:49], v[120:123], v[84:99]
	v_mfma_f32_32x32x16_bf16 v[68:83], v[50:53], v[120:123], v[68:83]
	v_mfma_f32_32x32x16_bf16 v[84:99], v[54:57], v[116:119], v[84:99]
	v_mfma_f32_32x32x16_bf16 v[68:83], v[58:61], v[116:119], v[68:83]
	ds_read_b128 v[46:49], v176 offset:0x80
	ds_read_b128 v[50:53], v176 offset:0x2080
	ds_read_b128 v[54:57], v177 offset:0x80
	ds_read_b128 v[58:61], v177 offset:0x2080
	s_waitcnt lgkmcnt(4)
	v_mfma_f32_32x32x16_bf16 v[84:99], v[42:45], v[112:115], v[84:99]
	v_mfma_f32_32x32x16_bf16 v[68:83], v[62:65], v[112:115], v[68:83]
	v_mfma_f32_32x32x16_bf16 v[84:99], v[132:135], v[108:111], v[84:99]
	v_mfma_f32_32x32x16_bf16 v[68:83], v[136:139], v[108:111], v[68:83]
	s_waitcnt lgkmcnt(0)
	v_mfma_f32_32x32x16_bf16 v[84:99], v[46:49], v[104:107], v[84:99]
	v_mfma_f32_32x32x16_bf16 v[68:83], v[50:53], v[104:107], v[68:83]
	v_mfma_f32_32x32x16_bf16 v[84:99], v[54:57], v[100:103], v[84:99]
	v_mfma_f32_32x32x16_bf16 v[68:83], v[58:61], v[100:103], v[68:83]
	s_add_i32 s8, 0, 0x10000
	s_waitcnt vmcnt(0)
	s_waitcnt vmcnt(3)
	ds_write_b128 v40, v[20:23] offset:16384
	s_waitcnt vmcnt(2)
	ds_write_b128 v41, v[24:27] offset:16384
	v_add_u32_e32 v20, s8, v180
	s_waitcnt vmcnt(1)
	ds_write_b128 v20, v[28:31]
	v_add_u32_e32 v20, s8, v181
	s_waitcnt vmcnt(0)
	ds_write_b128 v20, v[32:35]
	v_add_co_u32_e32 v20, vcc, s22, v38
	s_nop 1
	v_addc_co_u32_e32 v21, vcc, 0, v39, vcc
	global_load_dwordx4 v[132:135], v[20:21], off
	v_add_co_u32_e32 v20, vcc, s24, v38
	s_nop 1
	v_addc_co_u32_e32 v21, vcc, 0, v39, vcc
	global_load_dwordx4 v[140:143], v[20:21], off
	v_add_co_u32_e32 v20, vcc, s22, v36
	s_nop 1
	v_addc_co_u32_e32 v21, vcc, 0, v37, vcc
	global_load_dwordx4 v[136:139], v[20:21], off
	v_add_co_u32_e32 v20, vcc, s24, v36
	s_nop 1
	v_addc_co_u32_e32 v21, vcc, 0, v37, vcc
	global_load_dwordx4 v[144:147], v[20:21], off
	s_waitcnt lgkmcnt(0)
	s_barrier
	s_movk_i32 s8, 0x118
	s_cmp_lg_u32 0, -1
	v_and_or_b32 v20, v66, s8, v148
	s_cselect_b32 s8, 0, 0
	v_add3_u32 v173, v67, s8, v20
	v_mov_b64_e32 v[66:67], v[18:19]
	v_mov_b64_e32 v[50:51], v[18:19]
	v_mov_b64_e32 v[34:35], v[18:19]
	v_cmp_gt_u32_e64 s[38:39], 32, v169
	v_lshl_add_u32 v172, v165, 2, v171
	v_mov_b32_e32 v183, 0
	v_mov_b32_e32 v182, 0xf149f2ca
	v_mov_b64_e32 v[64:65], v[16:17]
	v_mov_b64_e32 v[62:63], v[14:15]
	v_mov_b64_e32 v[60:61], v[12:13]
	v_mov_b64_e32 v[58:59], v[10:11]
	v_mov_b64_e32 v[56:57], v[8:9]
	v_mov_b64_e32 v[54:55], v[6:7]
	v_mov_b64_e32 v[52:53], v[4:5]
	v_mov_b64_e32 v[48:49], v[16:17]
	v_mov_b64_e32 v[46:47], v[14:15]
	v_mov_b64_e32 v[44:45], v[12:13]
	v_mov_b64_e32 v[42:43], v[10:11]
	v_mov_b64_e32 v[40:41], v[8:9]
	v_mov_b64_e32 v[38:39], v[6:7]
	v_mov_b64_e32 v[36:37], v[4:5]
	v_mov_b64_e32 v[32:33], v[16:17]
	v_mov_b64_e32 v[30:31], v[14:15]
	v_mov_b64_e32 v[28:29], v[12:13]
	v_mov_b64_e32 v[26:27], v[10:11]
	v_mov_b64_e32 v[24:25], v[8:9]
	v_mov_b64_e32 v[22:23], v[6:7]
	v_mov_b64_e32 v[20:21], v[4:5]
	s_mov_b32 s51, 2
	v_max_f32_e32 v237, v84, v85
	v_max_f32_e32 v238, v68, v69
	v_max3_f32 v237, v237, v86, v87
	v_max3_f32 v238, v238, v70, v71
	v_max3_f32 v237, v237, v88, v89
	v_max3_f32 v238, v238, v72, v73
	v_max3_f32 v237, v237, v90, v91
	v_max3_f32 v238, v238, v74, v75
	v_max3_f32 v237, v237, v92, v93
	v_max3_f32 v238, v238, v76, v77
	v_max3_f32 v237, v237, v94, v95
	v_max3_f32 v238, v238, v78, v79
	v_max3_f32 v237, v237, v96, v97
	v_max3_f32 v238, v238, v80, v81
	v_max3_f32 v237, v237, v98, v99
	v_max3_f32 v238, v238, v82, v83
	v_max_f32_e32 v237, v237, v238
	v_mov_b32_e32 v238, v237
	s_nop 1
	v_permlane32_swap_b32_e32 v237, v238
	v_max_f32_e32 v237, v237, v238
	v_sub_f32_e32 v238, v237, v182
	v_cmp_ge_f32_e32 vcc, s23, v238
	v_max_f32_e32 v237, v182, v237
	s_cmp_eq_u64 vcc, exec
	s_cselect_b64 vcc, -1, 0
	v_sub_f32_e32 v239, v182, v237
	v_cndmask_b32_e32 v182, v237, v182, vcc
	v_mul_f32_e32 v237, 0xbe0293ee, v182
	v_fmamk_f32 v84, v84, 0x3e0293ee, v237
	v_fmamk_f32 v85, v85, 0x3e0293ee, v237
	v_fmamk_f32 v86, v86, 0x3e0293ee, v237
	v_fmamk_f32 v87, v87, 0x3e0293ee, v237
	v_fmamk_f32 v88, v88, 0x3e0293ee, v237
	v_fmamk_f32 v89, v89, 0x3e0293ee, v237
	v_fmamk_f32 v90, v90, 0x3e0293ee, v237
	v_fmamk_f32 v91, v91, 0x3e0293ee, v237
	v_fmamk_f32 v92, v92, 0x3e0293ee, v237
	v_fmamk_f32 v93, v93, 0x3e0293ee, v237
	v_fmamk_f32 v94, v94, 0x3e0293ee, v237
	v_fmamk_f32 v95, v95, 0x3e0293ee, v237
	v_fmamk_f32 v96, v96, 0x3e0293ee, v237
	v_fmamk_f32 v97, v97, 0x3e0293ee, v237
	v_fmamk_f32 v98, v98, 0x3e0293ee, v237
	v_fmamk_f32 v99, v99, 0x3e0293ee, v237
	v_fmamk_f32 v68, v68, 0x3e0293ee, v237
	v_fmamk_f32 v69, v69, 0x3e0293ee, v237
	v_fmamk_f32 v70, v70, 0x3e0293ee, v237
	v_fmamk_f32 v71, v71, 0x3e0293ee, v237
	v_fmamk_f32 v72, v72, 0x3e0293ee, v237
	v_fmamk_f32 v73, v73, 0x3e0293ee, v237
	v_fmamk_f32 v74, v74, 0x3e0293ee, v237
	v_fmamk_f32 v75, v75, 0x3e0293ee, v237
	v_fmamk_f32 v76, v76, 0x3e0293ee, v237
	v_fmamk_f32 v77, v77, 0x3e0293ee, v237
	v_fmamk_f32 v78, v78, 0x3e0293ee, v237
	v_fmamk_f32 v79, v79, 0x3e0293ee, v237
	v_fmamk_f32 v80, v80, 0x3e0293ee, v237
	v_fmamk_f32 v81, v81, 0x3e0293ee, v237
	v_fmamk_f32 v82, v82, 0x3e0293ee, v237
	v_fmac_f32_e32 v237, 0x3e0293ee, v83
.LBB0_629:
	v_exp_f32_e32 v83, v84
	v_exp_f32_e32 v84, v85
	v_exp_f32_e32 v85, v86
	v_add_f32_e32 v149, v84, v83
	v_exp_f32_e32 v86, v87
	v_add_f32_e32 v149, v85, v149
	v_exp_f32_e32 v87, v88
	v_add_f32_e32 v149, v86, v149
	v_exp_f32_e32 v88, v89
	v_add_f32_e32 v149, v87, v149
	v_exp_f32_e32 v89, v90
	v_add_f32_e32 v149, v88, v149
	v_exp_f32_e32 v90, v91
	v_add_f32_e32 v149, v89, v149
	v_exp_f32_e32 v91, v92
	v_add_f32_e32 v149, v90, v149
	v_exp_f32_e32 v92, v93
	v_add_f32_e32 v149, v91, v149
	v_exp_f32_e32 v93, v94
	v_add_f32_e32 v149, v92, v149
	v_exp_f32_e32 v94, v95
	v_add_f32_e32 v149, v93, v149
	v_exp_f32_e32 v95, v96
	v_add_f32_e32 v149, v94, v149
	v_exp_f32_e32 v96, v97
	v_add_f32_e32 v149, v95, v149
	v_exp_f32_e32 v97, v98
	v_add_f32_e32 v149, v96, v149
	v_exp_f32_e32 v98, v99
	v_add_f32_e32 v149, v97, v149
	v_exp_f32_e32 v99, v237
	v_add_f32_e32 v149, v98, v149
	v_exp_f32_e32 v68, v68
	v_exp_f32_e32 v69, v69
	v_add_f32_e32 v149, v68, v149
	v_exp_f32_e32 v70, v70
	v_add_f32_e32 v149, v69, v149
	v_exp_f32_e32 v71, v71
	v_add_f32_e32 v149, v70, v149
	v_exp_f32_e32 v72, v72
	v_add_f32_e32 v149, v71, v149
	v_exp_f32_e32 v73, v73
	v_add_f32_e32 v149, v72, v149
	v_exp_f32_e32 v74, v74
	v_add_f32_e32 v149, v73, v149
	v_exp_f32_e32 v75, v75
	v_add_f32_e32 v149, v74, v149
	v_exp_f32_e32 v76, v76
	v_add_f32_e32 v149, v75, v149
	v_exp_f32_e32 v77, v77
	v_add_f32_e32 v149, v76, v149
	v_exp_f32_e32 v78, v78
	v_add_f32_e32 v149, v77, v149
	v_exp_f32_e32 v79, v79
	v_add_f32_e32 v149, v78, v149
	v_exp_f32_e32 v80, v80
	v_add_f32_e32 v149, v79, v149
	v_exp_f32_e32 v81, v81
	v_add_f32_e32 v149, v80, v149
	v_exp_f32_e32 v82, v82
	v_add_f32_e32 v149, v81, v149
	v_mul_f32_e32 v239, 0x3e0293ee, v239
	v_add_f32_e32 v149, v82, v149
	v_exp_f32_e32 v239, v239
	v_add_f32_e32 v185, v99, v149
	v_cndmask_b32_e64 v184, v239, 1.0, vcc
	v_cvt_pk_bf16_f32 v148, v83, v84
	v_cvt_pk_bf16_f32 v149, v85, v86
	v_cvt_pk_bf16_f32 v150, v87, v88
	v_cvt_pk_bf16_f32 v151, v89, v90
	v_cvt_pk_bf16_f32 v152, v91, v92
	v_cvt_pk_bf16_f32 v153, v93, v94
	v_cvt_pk_bf16_f32 v154, v95, v96
	v_cvt_pk_bf16_f32 v155, v97, v98
	v_cvt_pk_bf16_f32 v156, v68, v69
	v_cvt_pk_bf16_f32 v157, v70, v71
	v_cvt_pk_bf16_f32 v158, v72, v73
	v_cvt_pk_bf16_f32 v159, v74, v75
	v_cvt_pk_bf16_f32 v160, v76, v77
	v_cvt_pk_bf16_f32 v161, v78, v79
	v_cvt_pk_bf16_f32 v162, v80, v81
	v_cvt_pk_bf16_f32 v163, v82, v99
	s_mov_b32 s53, s52
	s_cbranch_vccnz .LBB0_633
	s_and_saveexec_b64 s[16:17], s[38:39]
	ds_write_b32 v172, v184 offset:128
	s_or_b64 exec, exec, s[16:17]
	s_waitcnt lgkmcnt(0)
	v_add_u32_e32 v80, v171, v168
	ds_read_b128 v[68:71], v80 offset:224
	ds_read_b128 v[72:75], v80 offset:192
	ds_read_b128 v[76:79], v80 offset:160
	ds_read_b128 v[80:83], v80 offset:128
	s_waitcnt lgkmcnt(3)
	v_pk_mul_f32 v[16:17], v[16:17], v[68:69]
	s_waitcnt lgkmcnt(2)
	v_pk_mul_f32 v[12:13], v[12:13], v[72:73]
	s_waitcnt lgkmcnt(1)
	v_pk_mul_f32 v[8:9], v[8:9], v[76:77]
	v_pk_mul_f32 v[18:19], v[18:19], v[70:71]
	v_pk_mul_f32 v[14:15], v[14:15], v[74:75]
	v_pk_mul_f32 v[10:11], v[10:11], v[78:79]
	s_waitcnt lgkmcnt(0)
	v_pk_mul_f32 v[6:7], v[6:7], v[82:83]
	v_pk_mul_f32 v[4:5], v[4:5], v[80:81]
	v_pk_mul_f32 v[64:65], v[64:65], v[68:69]
	v_pk_mul_f32 v[60:61], v[60:61], v[72:73]
	v_pk_mul_f32 v[56:57], v[56:57], v[76:77]
	v_pk_mul_f32 v[66:67], v[66:67], v[70:71]
	v_pk_mul_f32 v[62:63], v[62:63], v[74:75]
	v_pk_mul_f32 v[58:59], v[58:59], v[78:79]
	v_pk_mul_f32 v[54:55], v[54:55], v[82:83]
	v_pk_mul_f32 v[52:53], v[52:53], v[80:81]
	v_pk_mul_f32 v[48:49], v[48:49], v[68:69]
	v_pk_mul_f32 v[44:45], v[44:45], v[72:73]
	v_pk_mul_f32 v[40:41], v[40:41], v[76:77]
	v_pk_mul_f32 v[50:51], v[50:51], v[70:71]
	v_pk_mul_f32 v[46:47], v[46:47], v[74:75]
	v_pk_mul_f32 v[42:43], v[42:43], v[78:79]
	v_pk_mul_f32 v[38:39], v[38:39], v[82:83]
	v_pk_mul_f32 v[36:37], v[36:37], v[80:81]
	v_pk_mul_f32 v[32:33], v[32:33], v[68:69]
	v_pk_mul_f32 v[28:29], v[28:29], v[72:73]
	v_pk_mul_f32 v[24:25], v[24:25], v[76:77]
	v_pk_mul_f32 v[34:35], v[34:35], v[70:71]
	v_pk_mul_f32 v[30:31], v[30:31], v[74:75]
	v_pk_mul_f32 v[26:27], v[26:27], v[78:79]
	v_pk_mul_f32 v[22:23], v[22:23], v[82:83]
	v_pk_mul_f32 v[20:21], v[20:21], v[80:81]
.LBB0_633:
	s_waitcnt lgkmcnt(0)
	s_barrier
	v_lshl_add_u32 v187, s53, 14, v173
	ds_read_b64_tr_b16 v[188:189], v187 offset:0
	ds_read_b64_tr_b16 v[190:191], v187 offset:0x800
	ds_read_b64_tr_b16 v[192:193], v187 offset:0x1000
	ds_read_b64_tr_b16 v[194:195], v187 offset:0x1800
	ds_read_b64_tr_b16 v[196:197], v187 offset:0x2000
	ds_read_b64_tr_b16 v[198:199], v187 offset:0x2800
	ds_read_b64_tr_b16 v[200:201], v187 offset:0x3000
	ds_read_b64_tr_b16 v[202:203], v187 offset:0x3800
	s_lshl_b32 s52, s49, 14
	v_add_u32_e32 v208, s52, v174
	ds_read_b128 v[68:71], v208 offset:0
	ds_read_b128 v[72:75], v208 offset:0x2000
	v_add_u32_e32 v209, s52, v175
	ds_read_b128 v[204:207], v209 offset:0
	ds_read_b128 v[216:219], v209 offset:0x2000
	v_add_u32_e32 v210, s52, v176
	ds_read_b128 v[220:223], v210 offset:0
	ds_read_b128 v[224:227], v210 offset:0x2000
	v_add_u32_e32 v211, s52, v177
	ds_read_b128 v[228:231], v211 offset:0
	ds_read_b128 v[232:235], v211 offset:0x2000
	s_waitcnt lgkmcnt(4)
	v_mfma_f32_32x32x16_bf16 v[84:99], v[68:71], v[128:131], 0
	v_mfma_f32_32x32x16_bf16 v[68:83], v[72:75], v[128:131], 0
	v_mfma_f32_32x32x16_bf16 v[84:99], v[204:207], v[124:127], v[84:99]
	v_mfma_f32_32x32x16_bf16 v[68:83], v[216:219], v[124:127], v[68:83]
	ds_read_b128 v[204:207], v208 offset:0x80
	ds_read_b128 v[216:219], v208 offset:0x2080
	ds_read_b128 v[236:239], v209 offset:0x80
	ds_read_b128 v[242:245], v209 offset:0x2080
	s_waitcnt lgkmcnt(4)
	v_mfma_f32_32x32x16_bf16 v[84:99], v[220:223], v[120:123], v[84:99]
	v_mfma_f32_32x32x16_bf16 v[68:83], v[224:227], v[120:123], v[68:83]
	v_mfma_f32_32x32x16_bf16 v[84:99], v[228:231], v[116:119], v[84:99]
	v_mfma_f32_32x32x16_bf16 v[68:83], v[232:235], v[116:119], v[68:83]
	ds_read_b128 v[220:223], v210 offset:0x80
	ds_read_b128 v[224:227], v210 offset:0x2080
	ds_read_b128 v[228:231], v211 offset:0x80
	ds_read_b128 v[232:235], v211 offset:0x2080
	s_waitcnt lgkmcnt(4)
	v_mfma_f32_32x32x16_bf16 v[84:99], v[204:207], v[112:115], v[84:99]
	v_mfma_f32_32x32x16_bf16 v[68:83], v[216:219], v[112:115], v[68:83]
	v_mfma_f32_32x32x16_bf16 v[84:99], v[236:239], v[108:111], v[84:99]
	v_mfma_f32_32x32x16_bf16 v[68:83], v[242:245], v[108:111], v[68:83]
	s_waitcnt lgkmcnt(0)
	v_mfma_f32_32x32x16_bf16 v[84:99], v[220:223], v[104:107], v[84:99]
	v_mfma_f32_32x32x16_bf16 v[68:83], v[224:227], v[104:107], v[68:83]
	v_mfma_f32_32x32x16_bf16 v[84:99], v[228:231], v[100:103], v[84:99]
	v_mfma_f32_32x32x16_bf16 v[68:83], v[232:235], v[100:103], v[68:83]
	ds_read_b64_tr_b16 v[204:205], v187 offset:0x200
	ds_read_b64_tr_b16 v[206:207], v187 offset:0xa00
	ds_read_b64_tr_b16 v[216:217], v187 offset:0x1200
	ds_read_b64_tr_b16 v[218:219], v187 offset:0x1a00
	ds_read_b64_tr_b16 v[220:221], v187 offset:0x2200
	ds_read_b64_tr_b16 v[222:223], v187 offset:0x2a00
	ds_read_b64_tr_b16 v[224:225], v187 offset:0x3200
	ds_read_b64_tr_b16 v[226:227], v187 offset:0x3a00
	s_waitcnt lgkmcnt(8)
	s_add_i32 s48, s48, 1
	s_cmp_eq_u32 s46, s48
	s_cbranch_scc1 .Lmy_attn_pv_plain
	v_mfma_f32_32x32x16_bf16 v[4:19], v[148:151], v[188:191], v[4:19]
	s_lshl_b32 s19, s51, 14
	v_add_u32_e32 v236, s19, v179
	s_waitcnt vmcnt(0)
	s_sub_i32 s8, s50, s47
	s_min_u32 s36, s50, s8
	s_lshl_b64 s[8:9], s[36:37], 10
	s_cmp_lt_u32 s50, s47
	s_cselect_b32 s16, s30, s20
	s_cselect_b32 s17, s31, s21
	s_cselect_b32 s36, s42, s26
	s_cselect_b32 s54, s43, s27
	v_mfma_f32_32x32x16_bf16 v[4:19], v[152:155], v[192:195], v[4:19]
	ds_write_b128 v236, v[144:147]
	v_add_u32_e32 v236, s19, v178
	s_add_u32 s16, s16, s8
	s_addc_u32 s17, s17, s9
	s_add_u32 s8, s36, s8
	s_addc_u32 s9, s54, s9
	v_mfma_f32_32x32x16_bf16 v[4:19], v[156:159], v[196:199], v[4:19]
	ds_write_b128 v236, v[136:139]
	v_add_u32_e32 v236, s19, v180
	v_max_f32_e32 v237, v84, v85
	v_max_f32_e32 v238, v68, v69
	v_max3_f32 v237, v237, v86, v87
	v_max3_f32 v238, v238, v70, v71
	v_mfma_f32_32x32x16_bf16 v[4:19], v[160:163], v[200:203], v[4:19]
	v_max3_f32 v237, v237, v88, v89
	v_max3_f32 v238, v238, v72, v73
	v_max3_f32 v237, v237, v90, v91
	v_max3_f32 v238, v238, v74, v75
	v_max3_f32 v237, v237, v92, v93
	ds_read_b64_tr_b16 v[188:189], v187 offset:0x400
	ds_read_b64_tr_b16 v[190:191], v187 offset:0xc00
	ds_read_b64_tr_b16 v[192:193], v187 offset:0x1400
	ds_read_b64_tr_b16 v[194:195], v187 offset:0x1c00
	ds_read_b64_tr_b16 v[196:197], v187 offset:0x2400
	ds_read_b64_tr_b16 v[198:199], v187 offset:0x2c00
	ds_read_b64_tr_b16 v[200:201], v187 offset:0x3400
	ds_read_b64_tr_b16 v[202:203], v187 offset:0x3c00
	s_waitcnt lgkmcnt(10)
	v_mfma_f32_32x32x16_bf16 v[52:67], v[148:151], v[204:207], v[52:67]
	ds_write_b128 v236, v[140:143] offset:49152
	v_add_u32_e32 v236, s19, v181
	v_max3_f32 v238, v238, v76, v77
	v_max3_f32 v237, v237, v94, v95
	v_max3_f32 v238, v238, v78, v79
	v_max3_f32 v237, v237, v96, v97
	v_mfma_f32_32x32x16_bf16 v[52:67], v[152:155], v[216:219], v[52:67]
	ds_write_b128 v236, v[132:135] offset:49152
	v_max3_f32 v238, v238, v80, v81
	v_max3_f32 v237, v237, v98, v99
	v_max3_f32 v238, v238, v82, v83
	v_max_f32_e32 v237, v237, v238
	v_mov_b32_e32 v238, v237
	v_mfma_f32_32x32x16_bf16 v[52:67], v[156:159], v[220:223], v[52:67]
	s_nop 1
	v_permlane32_swap_b32_e32 v237, v238
	v_max_f32_e32 v237, v237, v238
	v_sub_f32_e32 v238, v237, v182
	v_cmp_ge_f32_e32 vcc, s23, v238
	v_mfma_f32_32x32x16_bf16 v[52:67], v[160:163], v[224:227], v[52:67]
	v_max_f32_e32 v237, v182, v237
	s_cmp_eq_u64 vcc, exec
	s_cselect_b64 vcc, -1, 0
	v_sub_f32_e32 v239, v182, v237
	v_cndmask_b32_e32 v182, v237, v182, vcc
	v_mul_f32_e32 v237, 0xbe0293ee, v182
	ds_read_b64_tr_b16 v[204:205], v187 offset:0x600
	ds_read_b64_tr_b16 v[206:207], v187 offset:0xe00
	ds_read_b64_tr_b16 v[216:217], v187 offset:0x1600
	ds_read_b64_tr_b16 v[218:219], v187 offset:0x1e00
	ds_read_b64_tr_b16 v[220:221], v187 offset:0x2600
	ds_read_b64_tr_b16 v[222:223], v187 offset:0x2e00
	ds_read_b64_tr_b16 v[224:225], v187 offset:0x3600
	ds_read_b64_tr_b16 v[226:227], v187 offset:0x3e00
	s_waitcnt lgkmcnt(10)
	v_mfma_f32_32x32x16_bf16 v[36:51], v[148:151], v[188:191], v[36:51]
	global_load_dwordx4 v[144:147], v2, s[8:9]
	s_add_u32 s8, s8, 0x8000
	s_addc_u32 s9, s9, 0
	v_fmamk_f32 v84, v84, 0x3e0293ee, v237
	v_fmamk_f32 v85, v85, 0x3e0293ee, v237
	v_fmamk_f32 v86, v86, 0x3e0293ee, v237
	v_fmamk_f32 v87, v87, 0x3e0293ee, v237
	v_mfma_f32_32x32x16_bf16 v[36:51], v[152:155], v[192:195], v[36:51]
	global_load_dwordx4 v[136:139], v2, s[8:9]
	v_fmamk_f32 v88, v88, 0x3e0293ee, v237
	v_fmamk_f32 v89, v89, 0x3e0293ee, v237
	v_fmamk_f32 v90, v90, 0x3e0293ee, v237
	v_fmamk_f32 v91, v91, 0x3e0293ee, v237
	v_mfma_f32_32x32x16_bf16 v[36:51], v[156:159], v[196:199], v[36:51]
	global_load_dwordx4 v[140:143], v2, s[16:17]
	s_add_u32 s16, s16, 0x8000
	s_addc_u32 s17, s17, 0
	v_fmamk_f32 v92, v92, 0x3e0293ee, v237
	v_fmamk_f32 v93, v93, 0x3e0293ee, v237
	v_fmamk_f32 v94, v94, 0x3e0293ee, v237
	v_fmamk_f32 v95, v95, 0x3e0293ee, v237
	v_mfma_f32_32x32x16_bf16 v[36:51], v[160:163], v[200:203], v[36:51]
	global_load_dwordx4 v[132:135], v2, s[16:17]
	v_fmamk_f32 v96, v96, 0x3e0293ee, v237
	v_fmamk_f32 v97, v97, 0x3e0293ee, v237
	v_fmamk_f32 v98, v98, 0x3e0293ee, v237
	v_fmamk_f32 v99, v99, 0x3e0293ee, v237
	v_fmamk_f32 v68, v68, 0x3e0293ee, v237
	s_waitcnt lgkmcnt(0)
	v_mfma_f32_32x32x16_bf16 v[20:35], v[148:151], v[204:207], v[20:35]
	v_fmamk_f32 v69, v69, 0x3e0293ee, v237
	v_fmamk_f32 v70, v70, 0x3e0293ee, v237
	v_fmamk_f32 v71, v71, 0x3e0293ee, v237
	v_fmamk_f32 v72, v72, 0x3e0293ee, v237
	v_fmamk_f32 v73, v73, 0x3e0293ee, v237
	v_mfma_f32_32x32x16_bf16 v[20:35], v[152:155], v[216:219], v[20:35]
	v_fmamk_f32 v74, v74, 0x3e0293ee, v237
	v_fmamk_f32 v75, v75, 0x3e0293ee, v237
	v_fmamk_f32 v76, v76, 0x3e0293ee, v237
	v_fmamk_f32 v77, v77, 0x3e0293ee, v237
	v_fmamk_f32 v78, v78, 0x3e0293ee, v237
	v_mfma_f32_32x32x16_bf16 v[20:35], v[156:159], v[220:223], v[20:35]
	v_fmamk_f32 v79, v79, 0x3e0293ee, v237
	v_fmamk_f32 v80, v80, 0x3e0293ee, v237
	v_fmamk_f32 v81, v81, 0x3e0293ee, v237
	v_fmamk_f32 v82, v82, 0x3e0293ee, v237
	v_fmac_f32_e32 v237, 0x3e0293ee, v83
	v_mfma_f32_32x32x16_bf16 v[20:35], v[160:163], v[224:227], v[20:35]

.Lmy_attn_pv_plain:
	v_mfma_f32_32x32x16_bf16 v[4:19], v[148:151], v[188:191], v[4:19]
	s_lshl_b32 s19, s51, 14
	s_add_i32 s8, s19, 0
	v_add_u32_e32 v236, s8, v179
	s_waitcnt vmcnt(0)
	v_mfma_f32_32x32x16_bf16 v[4:19], v[152:155], v[192:195], v[4:19]
	ds_write_b128 v236, v[144:147]
	v_add_u32_e32 v236, s8, v178
	v_mfma_f32_32x32x16_bf16 v[4:19], v[156:159], v[196:199], v[4:19]
	ds_write_b128 v236, v[136:139]
	v_add_u32_e32 v236, s8, v180
	v_mfma_f32_32x32x16_bf16 v[4:19], v[160:163], v[200:203], v[4:19]
	ds_read_b64_tr_b16 v[188:189], v187 offset:0x400
	ds_read_b64_tr_b16 v[190:191], v187 offset:0xc00
	ds_read_b64_tr_b16 v[192:193], v187 offset:0x1400
	ds_read_b64_tr_b16 v[194:195], v187 offset:0x1c00
	ds_read_b64_tr_b16 v[196:197], v187 offset:0x2400
	ds_read_b64_tr_b16 v[198:199], v187 offset:0x2c00
	ds_read_b64_tr_b16 v[200:201], v187 offset:0x3400
	ds_read_b64_tr_b16 v[202:203], v187 offset:0x3c00
	s_waitcnt lgkmcnt(10)
	v_mfma_f32_32x32x16_bf16 v[52:67], v[148:151], v[204:207], v[52:67]
	ds_write_b128 v236, v[140:143] offset:49152
	v_add_u32_e32 v236, s8, v181
	v_mfma_f32_32x32x16_bf16 v[52:67], v[152:155], v[216:219], v[52:67]
	ds_write_b128 v236, v[132:135] offset:49152
	v_mfma_f32_32x32x16_bf16 v[52:67], v[156:159], v[220:223], v[52:67]
	s_sub_i32 s8, s50, s47
	s_min_u32 s36, s50, s8
	s_lshl_b64 s[8:9], s[36:37], 10
	s_cmp_lt_u32 s50, s47
	s_cselect_b32 s16, s30, s20
	s_cselect_b32 s17, s31, s21
	v_mfma_f32_32x32x16_bf16 v[52:67], v[160:163], v[224:227], v[52:67]
	ds_read_b64_tr_b16 v[204:205], v187 offset:0x600
	ds_read_b64_tr_b16 v[206:207], v187 offset:0xe00
	ds_read_b64_tr_b16 v[216:217], v187 offset:0x1600
	ds_read_b64_tr_b16 v[218:219], v187 offset:0x1e00
	ds_read_b64_tr_b16 v[220:221], v187 offset:0x2600
	ds_read_b64_tr_b16 v[222:223], v187 offset:0x2e00
	ds_read_b64_tr_b16 v[224:225], v187 offset:0x3600
	ds_read_b64_tr_b16 v[226:227], v187 offset:0x3e00
	s_waitcnt lgkmcnt(10)
	v_mfma_f32_32x32x16_bf16 v[36:51], v[148:151], v[188:191], v[36:51]
	s_cselect_b32 s36, s42, s26
	s_cselect_b32 s54, s43, s27
	s_add_u32 s16, s16, s8
	s_addc_u32 s17, s17, s9
	s_add_u32 s8, s36, s8
	s_addc_u32 s9, s54, s9
	v_mfma_f32_32x32x16_bf16 v[36:51], v[152:155], v[192:195], v[36:51]
	global_load_dwordx4 v[144:147], v2, s[8:9]
	s_add_u32 s8, s8, 0x8000
	s_addc_u32 s9, s9, 0
	v_mfma_f32_32x32x16_bf16 v[36:51], v[156:159], v[196:199], v[36:51]
	global_load_dwordx4 v[136:139], v2, s[8:9]
	global_load_dwordx4 v[140:143], v2, s[16:17]
	v_mfma_f32_32x32x16_bf16 v[36:51], v[160:163], v[200:203], v[36:51]
	s_add_u32 s16, s16, 0x8000
	s_addc_u32 s17, s17, 0
	global_load_dwordx4 v[132:135], v2, s[16:17]
	s_waitcnt lgkmcnt(0)
	v_mfma_f32_32x32x16_bf16 v[20:35], v[148:151], v[204:207], v[20:35]
	v_mfma_f32_32x32x16_bf16 v[20:35], v[152:155], v[216:219], v[20:35]
	v_mfma_f32_32x32x16_bf16 v[20:35], v[156:159], v[220:223], v[20:35]
	v_mfma_f32_32x32x16_bf16 v[20:35], v[160:163], v[224:227], v[20:35]
	s_branch .LBB0_635
